# SSD forward output: d_skip V values and f_wi scalars read from LDS in one batch instead of 20 serialized reads
# baseline (speedup 1.0000x reference)
; __device__ __forceinline__ float bf2f(unsigned h) { return __uint_as_float(h << 16); }
; template <bool ISM>
; __device__ void scan_item(const Params& p, int l, int item, unsigned char* lds) {
;     ...
;           for (int j = 0; j < 4; ++j) { const int tl = fq * 4 + j, t = 16 * wid + tl; const float wi = f_wi[t];
;               float inv = 1.f;
;               if (ISM) { const float qn = __shfl(ia[NT - 1][j], lane & 48, 64); const float dn = __shfl(dsum, tl, 64); inv = __builtin_amdgcn_rcpf(fmaxf(fabsf(wi * qn + dn), f_em[t])); }
;               u16* dst = obase + (size_t)od[j];
;               float v[4];
; #pragma unroll
;               for (int n = 0; n < 4; ++n) { v[n] = (wi * ia[n][j] + ib[n][j]) * inv; if (!ISM && dir == 0) v[n] += Dh * bf2f(Vs[t * LDV + n * 16 + fr]); }
.LBB0_118:
	s_andn2_b64 vcc, exec, s[6:7]
	s_cbranch_vccnz .Lssd_noskipv
	ds_read_u16 v96, v224 offset:34816
	ds_read_u16 v97, v224 offset:34848
	ds_read_u16 v98, v224 offset:34880
	ds_read_u16 v99, v224 offset:34912
	ds_read_u16 v100, v224 offset:34992
	ds_read_u16 v101, v224 offset:35024
	ds_read_u16 v102, v224 offset:35056
	ds_read_u16 v103, v224 offset:35088
	ds_read_u16 v108, v224 offset:35168
	ds_read_u16 v109, v224 offset:35200
	ds_read_u16 v110, v224 offset:35232
	ds_read_u16 v111, v224 offset:35264
	ds_read_u16 v120, v224 offset:35344
	ds_read_u16 v121, v224 offset:35376
	ds_read_u16 v122, v224 offset:35408
	ds_read_u16 v123, v224 offset:35440
.Lssd_noskipv:
	ds_read_b32 v240, v181
	ds_read_b32 v241, v183
	ds_read_b32 v242, v185
	ds_read_b32 v88, v179
	v_cndmask_b32_e64 v89, 0, 1, s[6:7]
	v_cmp_ne_u32_e64 s[18:19], 1, v89
	s_andn2_b64 vcc, exec, s[6:7]
	s_waitcnt lgkmcnt(0)
	v_fma_f32 v60, v60, v88, v68
	s_cbranch_vccnz .LBB0_122
	v_mov_b32_e32 v68, v96
	v_lshlrev_b32_e32 v68, 16, v68
	v_fmac_f32_e32 v60, v147, v68
	s_and_b64 vcc, exec, s[18:19]
	v_fma_f32 v64, v64, v88, v72
	s_cbranch_vccz .LBB0_123

; __device__ __forceinline__ float bf2f(unsigned h) { return __uint_as_float(h << 16); }
; __device__ __forceinline__ unsigned pk2(float lo, float hi) { const f32x2_t v = {lo, hi}; return __builtin_bit_cast(unsigned, __builtin_convertvector(v, bf16x2_t)); }
; template <bool ISM>
; __device__ void scan_item(const Params& p, int l, int item, unsigned char* lds) {
;     ...
;               u16* dst = obase + (size_t)od[j];
;               float v[4];
; #pragma unroll
;               for (int n = 0; n < 4; ++n) { v[n] = (wi * ia[n][j] + ib[n][j]) * inv; if (!ISM && dir == 0) v[n] += Dh * bf2f(Vs[t * LDV + n * 16 + fr]); }
;               const unsigned p01 = pk2(v[0], v[1]), p23 = pk2(v[2], v[3]);
;               dst[0] = (u16)(p01 & 0xFFFFu); dst[16] = (u16)(p01 >> 16); dst[32] = (u16)(p23 & 0xFFFFu); dst[48] = (u16)(p23 >> 16); } }
.LBB0_121:
	v_mov_b32_e32 v72, v98
	v_lshlrev_b32_e32 v72, 16, v72
	v_fmac_f32_e32 v68, v147, v72
	s_and_b64 vcc, exec, s[18:19]
	v_fma_f32 v56, v56, v88, v84
	s_cbranch_vccz .LBB0_125
	s_branch .LBB0_126

; __device__ __forceinline__ float bf2f(unsigned h) { return __uint_as_float(h << 16); }
; __device__ __forceinline__ unsigned pk2(float lo, float hi) { const f32x2_t v = {lo, hi}; return __builtin_bit_cast(unsigned, __builtin_convertvector(v, bf16x2_t)); }
; template <bool ISM>
; __device__ void scan_item(const Params& p, int l, int item, unsigned char* lds) {
;     ...
;               u16* dst = obase + (size_t)od[j];
;               float v[4];
; #pragma unroll
;               for (int n = 0; n < 4; ++n) { v[n] = (wi * ia[n][j] + ib[n][j]) * inv; if (!ISM && dir == 0) v[n] += Dh * bf2f(Vs[t * LDV + n * 16 + fr]); }
;               const unsigned p01 = pk2(v[0], v[1]), p23 = pk2(v[2], v[3]);
;               dst[0] = (u16)(p01 & 0xFFFFu); dst[16] = (u16)(p01 >> 16); dst[32] = (u16)(p23 & 0xFFFFu); dst[48] = (u16)(p23 >> 16); } }
.LBB0_123:
	v_mov_b32_e32 v68, v97
	v_lshlrev_b32_e32 v68, 16, v68
	v_fmac_f32_e32 v64, v147, v68
	s_and_b64 vcc, exec, s[18:19]
	v_fma_f32 v68, v80, v88, v76
	s_cbranch_vccz .LBB0_121

; __device__ __forceinline__ float bf2f(unsigned h) { return __uint_as_float(h << 16); }
; __device__ __forceinline__ unsigned pk2(float lo, float hi) { const f32x2_t v = {lo, hi}; return __builtin_bit_cast(unsigned, __builtin_convertvector(v, bf16x2_t)); }
; template <bool ISM>
; __device__ void scan_item(const Params& p, int l, int item, unsigned char* lds) {
;     ...
;           for (int j = 0; j < 4; ++j) { const int tl = fq * 4 + j, t = 16 * wid + tl; const float wi = f_wi[t];
;               float inv = 1.f;
;               if (ISM) { const float qn = __shfl(ia[NT - 1][j], lane & 48, 64); const float dn = __shfl(dsum, tl, 64); inv = __builtin_amdgcn_rcpf(fmaxf(fabsf(wi * qn + dn), f_em[t])); }
;               u16* dst = obase + (size_t)od[j];
;               float v[4];
; #pragma unroll
;               for (int n = 0; n < 4; ++n) { v[n] = (wi * ia[n][j] + ib[n][j]) * inv; if (!ISM && dir == 0) v[n] += Dh * bf2f(Vs[t * LDV + n * 16 + fr]); }
;               const unsigned p01 = pk2(v[0], v[1]), p23 = pk2(v[2], v[3]);
;               dst[0] = (u16)(p01 & 0xFFFFu); dst[16] = (u16)(p01 >> 16); dst[32] = (u16)(p23 & 0xFFFFu); dst[48] = (u16)(p23 >> 16); } }
.LBB0_125:
	v_mov_b32_e32 v72, v99
	v_lshlrev_b32_e32 v72, 16, v72
	v_fmac_f32_e32 v56, v147, v72
.LBB0_126:
	v_cvt_pk_bf16_f32 v64, v60, v64
	v_mov_b32_e32 v60, v240
	v_mov_b32_e32 v199, v149
	v_lshl_add_u64 v[88:89], v[198:199], 1, s[30:31]
	v_cvt_pk_bf16_f32 v56, v68, v56
	global_store_short v[88:89], v64, off
	global_store_short_d16_hi v[88:89], v64, off offset:32
	global_store_short v[88:89], v56, off offset:64
	global_store_short_d16_hi v[88:89], v56, off offset:96
	s_and_b64 vcc, exec, s[18:19]
	s_waitcnt lgkmcnt(0)
	v_fma_f32 v56, v61, v60, v69
	s_cbranch_vccnz .LBB0_130
	v_mov_b32_e32 v61, v100
	v_lshlrev_b32_e32 v61, 16, v61
	v_fmac_f32_e32 v56, v147, v61
	s_and_b64 vcc, exec, s[18:19]
	v_fma_f32 v61, v65, v60, v73
	s_cbranch_vccz .LBB0_131

; __device__ __forceinline__ float bf2f(unsigned h) { return __uint_as_float(h << 16); }
; __device__ __forceinline__ unsigned pk2(float lo, float hi) { const f32x2_t v = {lo, hi}; return __builtin_bit_cast(unsigned, __builtin_convertvector(v, bf16x2_t)); }
; template <bool ISM>
; __device__ void scan_item(const Params& p, int l, int item, unsigned char* lds) {
;     ...
;               u16* dst = obase + (size_t)od[j];
;               float v[4];
; #pragma unroll
;               for (int n = 0; n < 4; ++n) { v[n] = (wi * ia[n][j] + ib[n][j]) * inv; if (!ISM && dir == 0) v[n] += Dh * bf2f(Vs[t * LDV + n * 16 + fr]); }
;               const unsigned p01 = pk2(v[0], v[1]), p23 = pk2(v[2], v[3]);
;               dst[0] = (u16)(p01 & 0xFFFFu); dst[16] = (u16)(p01 >> 16); dst[32] = (u16)(p23 & 0xFFFFu); dst[48] = (u16)(p23 >> 16); } }
.LBB0_129:
	v_mov_b32_e32 v65, v102
	v_lshlrev_b32_e32 v65, 16, v65
	v_fmac_f32_e32 v64, v147, v65
	s_and_b64 vcc, exec, s[18:19]
	v_fma_f32 v57, v57, v60, v85
	s_cbranch_vccz .LBB0_133
	s_branch .LBB0_134

; __device__ __forceinline__ float bf2f(unsigned h) { return __uint_as_float(h << 16); }
; __device__ __forceinline__ unsigned pk2(float lo, float hi) { const f32x2_t v = {lo, hi}; return __builtin_bit_cast(unsigned, __builtin_convertvector(v, bf16x2_t)); }
; template <bool ISM>
; __device__ void scan_item(const Params& p, int l, int item, unsigned char* lds) {
;     ...
;               u16* dst = obase + (size_t)od[j];
;               float v[4];
; #pragma unroll
;               for (int n = 0; n < 4; ++n) { v[n] = (wi * ia[n][j] + ib[n][j]) * inv; if (!ISM && dir == 0) v[n] += Dh * bf2f(Vs[t * LDV + n * 16 + fr]); }
;               const unsigned p01 = pk2(v[0], v[1]), p23 = pk2(v[2], v[3]);
;               dst[0] = (u16)(p01 & 0xFFFFu); dst[16] = (u16)(p01 >> 16); dst[32] = (u16)(p23 & 0xFFFFu); dst[48] = (u16)(p23 >> 16); } }
.LBB0_131:
	v_mov_b32_e32 v64, v101
	v_lshlrev_b32_e32 v64, 16, v64
	v_fmac_f32_e32 v61, v147, v64
	s_and_b64 vcc, exec, s[18:19]
	v_fma_f32 v64, v81, v60, v77
	s_cbranch_vccz .LBB0_129

; __device__ __forceinline__ float bf2f(unsigned h) { return __uint_as_float(h << 16); }
; __device__ __forceinline__ unsigned pk2(float lo, float hi) { const f32x2_t v = {lo, hi}; return __builtin_bit_cast(unsigned, __builtin_convertvector(v, bf16x2_t)); }
; template <bool ISM>
; __device__ void scan_item(const Params& p, int l, int item, unsigned char* lds) {
;     ...
;           for (int j = 0; j < 4; ++j) { const int tl = fq * 4 + j, t = 16 * wid + tl; const float wi = f_wi[t];
;               float inv = 1.f;
;               if (ISM) { const float qn = __shfl(ia[NT - 1][j], lane & 48, 64); const float dn = __shfl(dsum, tl, 64); inv = __builtin_amdgcn_rcpf(fmaxf(fabsf(wi * qn + dn), f_em[t])); }
;               u16* dst = obase + (size_t)od[j];
;               float v[4];
; #pragma unroll
;               for (int n = 0; n < 4; ++n) { v[n] = (wi * ia[n][j] + ib[n][j]) * inv; if (!ISM && dir == 0) v[n] += Dh * bf2f(Vs[t * LDV + n * 16 + fr]); }
;               const unsigned p01 = pk2(v[0], v[1]), p23 = pk2(v[2], v[3]);
;               dst[0] = (u16)(p01 & 0xFFFFu); dst[16] = (u16)(p01 >> 16); dst[32] = (u16)(p23 & 0xFFFFu); dst[48] = (u16)(p23 >> 16); } }
.LBB0_133:
	v_mov_b32_e32 v60, v103
	v_lshlrev_b32_e32 v60, 16, v60
	v_fmac_f32_e32 v57, v147, v60
.LBB0_134:
	v_cvt_pk_bf16_f32 v60, v64, v57
	v_mov_b32_e32 v57, v241
	v_mov_b32_e32 v197, v149
	v_lshl_add_u64 v[68:69], v[196:197], 1, s[30:31]
	v_cvt_pk_bf16_f32 v56, v56, v61
	global_store_short v[68:69], v56, off
	global_store_short_d16_hi v[68:69], v56, off offset:32
	global_store_short v[68:69], v60, off offset:64
	global_store_short_d16_hi v[68:69], v60, off offset:96
	s_and_b64 vcc, exec, s[18:19]
	s_waitcnt lgkmcnt(0)
	v_fma_f32 v56, v62, v57, v70
	s_cbranch_vccnz .LBB0_138
	v_mov_b32_e32 v60, v108
	v_lshlrev_b32_e32 v60, 16, v60
	v_fmac_f32_e32 v56, v147, v60
	s_and_b64 vcc, exec, s[18:19]
	v_fma_f32 v60, v66, v57, v74
	s_cbranch_vccz .LBB0_139

; __device__ __forceinline__ float bf2f(unsigned h) { return __uint_as_float(h << 16); }
; __device__ __forceinline__ unsigned pk2(float lo, float hi) { const f32x2_t v = {lo, hi}; return __builtin_bit_cast(unsigned, __builtin_convertvector(v, bf16x2_t)); }
; template <bool ISM>
; __device__ void scan_item(const Params& p, int l, int item, unsigned char* lds) {
;     ...
;               u16* dst = obase + (size_t)od[j];
;               float v[4];
; #pragma unroll
;               for (int n = 0; n < 4; ++n) { v[n] = (wi * ia[n][j] + ib[n][j]) * inv; if (!ISM && dir == 0) v[n] += Dh * bf2f(Vs[t * LDV + n * 16 + fr]); }
;               const unsigned p01 = pk2(v[0], v[1]), p23 = pk2(v[2], v[3]);
;               dst[0] = (u16)(p01 & 0xFFFFu); dst[16] = (u16)(p01 >> 16); dst[32] = (u16)(p23 & 0xFFFFu); dst[48] = (u16)(p23 >> 16); } }
.LBB0_137:
	v_mov_b32_e32 v62, v110
	v_lshlrev_b32_e32 v62, 16, v62
	v_fmac_f32_e32 v61, v147, v62
	s_and_b64 vcc, exec, s[18:19]
	v_fma_f32 v57, v58, v57, v86
	s_cbranch_vccz .LBB0_141
	s_branch .LBB0_142

; __device__ __forceinline__ float bf2f(unsigned h) { return __uint_as_float(h << 16); }
; __device__ __forceinline__ unsigned pk2(float lo, float hi) { const f32x2_t v = {lo, hi}; return __builtin_bit_cast(unsigned, __builtin_convertvector(v, bf16x2_t)); }
; template <bool ISM>
; __device__ void scan_item(const Params& p, int l, int item, unsigned char* lds) {
;     ...
;               u16* dst = obase + (size_t)od[j];
;               float v[4];
; #pragma unroll
;               for (int n = 0; n < 4; ++n) { v[n] = (wi * ia[n][j] + ib[n][j]) * inv; if (!ISM && dir == 0) v[n] += Dh * bf2f(Vs[t * LDV + n * 16 + fr]); }
;               const unsigned p01 = pk2(v[0], v[1]), p23 = pk2(v[2], v[3]);
;               dst[0] = (u16)(p01 & 0xFFFFu); dst[16] = (u16)(p01 >> 16); dst[32] = (u16)(p23 & 0xFFFFu); dst[48] = (u16)(p23 >> 16); } }
.LBB0_139:
	v_mov_b32_e32 v61, v109
	v_lshlrev_b32_e32 v61, 16, v61
	v_fmac_f32_e32 v60, v147, v61
	s_and_b64 vcc, exec, s[18:19]
	v_fma_f32 v61, v82, v57, v78
	s_cbranch_vccz .LBB0_137

; __device__ __forceinline__ float bf2f(unsigned h) { return __uint_as_float(h << 16); }
; __device__ __forceinline__ unsigned pk2(float lo, float hi) { const f32x2_t v = {lo, hi}; return __builtin_bit_cast(unsigned, __builtin_convertvector(v, bf16x2_t)); }
; template <bool ISM>
; __device__ void scan_item(const Params& p, int l, int item, unsigned char* lds) {
;     ...
;           for (int j = 0; j < 4; ++j) { const int tl = fq * 4 + j, t = 16 * wid + tl; const float wi = f_wi[t];
;               float inv = 1.f;
;               if (ISM) { const float qn = __shfl(ia[NT - 1][j], lane & 48, 64); const float dn = __shfl(dsum, tl, 64); inv = __builtin_amdgcn_rcpf(fmaxf(fabsf(wi * qn + dn), f_em[t])); }
;               u16* dst = obase + (size_t)od[j];
;               float v[4];
; #pragma unroll
;               for (int n = 0; n < 4; ++n) { v[n] = (wi * ia[n][j] + ib[n][j]) * inv; if (!ISM && dir == 0) v[n] += Dh * bf2f(Vs[t * LDV + n * 16 + fr]); }
;               const unsigned p01 = pk2(v[0], v[1]), p23 = pk2(v[2], v[3]);
;               dst[0] = (u16)(p01 & 0xFFFFu); dst[16] = (u16)(p01 >> 16); dst[32] = (u16)(p23 & 0xFFFFu); dst[48] = (u16)(p23 >> 16); } }
.LBB0_141:
	v_mov_b32_e32 v58, v111
	v_lshlrev_b32_e32 v58, 16, v58
	v_fmac_f32_e32 v57, v147, v58
.LBB0_142:
	v_cvt_pk_bf16_f32 v58, v56, v60
	v_mov_b32_e32 v56, v242
	v_mov_b32_e32 v195, v149
	v_lshl_add_u64 v[64:65], v[194:195], 1, s[30:31]
	s_and_b64 vcc, exec, s[18:19]
	v_cvt_pk_bf16_f32 v57, v61, v57
	s_waitcnt lgkmcnt(0)
	v_fmac_f32_e32 v71, v63, v56
	global_store_short v[64:65], v58, off
	global_store_short_d16_hi v[64:65], v58, off offset:32
	global_store_short v[64:65], v57, off offset:64
	global_store_short_d16_hi v[64:65], v57, off offset:96
	s_cbranch_vccnz .LBB0_146
	v_mov_b32_e32 v57, v120
	v_lshlrev_b32_e32 v57, 16, v57
	v_fmac_f32_e32 v71, v147, v57
	s_and_b64 vcc, exec, s[18:19]
	v_fmac_f32_e32 v75, v67, v56
	s_cbranch_vccz .LBB0_147

; __device__ __forceinline__ float bf2f(unsigned h) { return __uint_as_float(h << 16); }
; __device__ __forceinline__ unsigned pk2(float lo, float hi) { const f32x2_t v = {lo, hi}; return __builtin_bit_cast(unsigned, __builtin_convertvector(v, bf16x2_t)); }
; template <bool ISM>
; __device__ void scan_item(const Params& p, int l, int item, unsigned char* lds) {
;     ...
;               u16* dst = obase + (size_t)od[j];
;               float v[4];
; #pragma unroll
;               for (int n = 0; n < 4; ++n) { v[n] = (wi * ia[n][j] + ib[n][j]) * inv; if (!ISM && dir == 0) v[n] += Dh * bf2f(Vs[t * LDV + n * 16 + fr]); }
;               const unsigned p01 = pk2(v[0], v[1]), p23 = pk2(v[2], v[3]);
;               dst[0] = (u16)(p01 & 0xFFFFu); dst[16] = (u16)(p01 >> 16); dst[32] = (u16)(p23 & 0xFFFFu); dst[48] = (u16)(p23 >> 16); } }
.LBB0_145:
	v_mov_b32_e32 v57, v122
	v_lshlrev_b32_e32 v57, 16, v57
	v_fmac_f32_e32 v79, v147, v57
	s_and_b64 vcc, exec, s[18:19]
	v_fmac_f32_e32 v87, v59, v56
	s_cbranch_vccnz .LBB0_30
	s_branch .LBB0_149

; __device__ __forceinline__ float bf2f(unsigned h) { return __uint_as_float(h << 16); }
; __device__ __forceinline__ unsigned pk2(float lo, float hi) { const f32x2_t v = {lo, hi}; return __builtin_bit_cast(unsigned, __builtin_convertvector(v, bf16x2_t)); }
; template <bool ISM>
; __device__ void scan_item(const Params& p, int l, int item, unsigned char* lds) {
;     ...
;               u16* dst = obase + (size_t)od[j];
;               float v[4];
; #pragma unroll
;               for (int n = 0; n < 4; ++n) { v[n] = (wi * ia[n][j] + ib[n][j]) * inv; if (!ISM && dir == 0) v[n] += Dh * bf2f(Vs[t * LDV + n * 16 + fr]); }
;               const unsigned p01 = pk2(v[0], v[1]), p23 = pk2(v[2], v[3]);
;               dst[0] = (u16)(p01 & 0xFFFFu); dst[16] = (u16)(p01 >> 16); dst[32] = (u16)(p23 & 0xFFFFu); dst[48] = (u16)(p23 >> 16); } }
.LBB0_147:
	v_mov_b32_e32 v57, v121
	v_lshlrev_b32_e32 v57, 16, v57
	v_fmac_f32_e32 v75, v147, v57
	s_and_b64 vcc, exec, s[18:19]
	v_fmac_f32_e32 v79, v83, v56
	s_cbranch_vccz .LBB0_145

; __device__ __forceinline__ float bf2f(unsigned h) { return __uint_as_float(h << 16); }
; __device__ __forceinline__ unsigned pk2(float lo, float hi) { const f32x2_t v = {lo, hi}; return __builtin_bit_cast(unsigned, __builtin_convertvector(v, bf16x2_t)); }
; template <bool ISM>
; __device__ void scan_item(const Params& p, int l, int item, unsigned char* lds) {
;     ...
;               u16* dst = obase + (size_t)od[j];
;               float v[4];
; #pragma unroll
;               for (int n = 0; n < 4; ++n) { v[n] = (wi * ia[n][j] + ib[n][j]) * inv; if (!ISM && dir == 0) v[n] += Dh * bf2f(Vs[t * LDV + n * 16 + fr]); }
;               const unsigned p01 = pk2(v[0], v[1]), p23 = pk2(v[2], v[3]);
;               dst[0] = (u16)(p01 & 0xFFFFu); dst[16] = (u16)(p01 >> 16); dst[32] = (u16)(p23 & 0xFFFFu); dst[48] = (u16)(p23 >> 16); } }
.LBB0_149:
	v_mov_b32_e32 v56, v123
	v_lshlrev_b32_e32 v56, 16, v56
	v_fmac_f32_e32 v87, v147, v56
	s_branch .LBB0_30
